# P8 GEMM K-loop: phase pairs merged (8 barriers per iteration, LDS reads retired before each barrier) and LDS-DMA with SGPR base + 32-bit offset addressing; on top of v138
# baseline (speedup 1.0000x reference)
; #define PG8_STAGE(bufoff, gbase, voff) do { _Pragma("unroll") for (int _i = 0; _i < 2; ++_i) \
;     __builtin_amdgcn_global_load_lds((const unsigned*)((const char*)(gbase) + (voff)[_i]), (LAS unsigned*)(lds + (bufoff) + ldsw + _i * 8192), 16, 0, 0); } while (0)
; #define PG8_LDA(dst, b, h) do { _Pragma("unroll") for (int m = 0; m < 4; ++m) _Pragma("unroll") for (int k = 0; k < 2; ++k) dst[m][k] = *(const LAS bf16x8*)(lds + PG8_SA(b, h) + aoff + m * 2048 + k * 1024); } while (0)
; #define PG8_LDB(dst, b, h) do { _Pragma("unroll") for (int n = 0; n < 2; ++n) _Pragma("unroll") for (int k = 0; k < 2; ++k) dst[n][k] = *(const LAS bf16x8*)(lds + PG8_SB(b, h) + boff + n * 2048 + k * 1024); } while (0)
; #define PG8_MMA(ai, bj, At, Bt) do { __builtin_amdgcn_s_setprio(1); _Pragma("unroll") for (int m = 0; m < 4; ++m) _Pragma("unroll") for (int n = 0; n < 2; ++n) _Pragma("unroll") for (int k = 0; k < 2; ++k) \
;     acc[ai][bj][m][n] = __builtin_amdgcn_mfma_f32_16x16x32_bf16(Bt[n][k], At[m][k], acc[ai][bj][m][n], 0, 0, 0); __builtin_amdgcn_s_setprio(0); } while (0)
; #define PG8_WAIT_V(n) asm volatile("s_waitcnt vmcnt(" #n ")" ::: "memory")
; #define PG8_WAIT_L(n) asm volatile("s_waitcnt lgkmcnt(" #n ")" ::: "memory")
; #define PG8_BAR __builtin_amdgcn_s_barrier()
; #define PG8_SCHED __builtin_amdgcn_sched_barrier(0)
; template <class Epi>
; __device__ __forceinline__ void gemm_phase(LAS unsigned char* lds, const Gemm g, const StaticOrder& S, const Epi& E) {
;     ...
;       PG8_LDB(B0, 0, 0); PG8_SCHED; PG8_LDA(At, 0, 0); PG8_STAGE(PG8_SA(1, 1), a1 + hstep, voffA);
;       PG8_WAIT_L(8); PG8_BAR; PG8_WAIT_L(0); PG8_MMA(0, 0, At, B0); PG8_BAR; PG8_SCHED;
;       PG8_LDB(B1, 0, 1); PG8_STAGE(PG8_SB(0, 0), b2, voffB);
;       PG8_BAR; PG8_WAIT_L(0); PG8_MMA(0, 1, At, B1); PG8_BAR;
;       PG8_LDA(At, 0, 1); PG8_STAGE(PG8_SA(0, 0), a2, voffA);
;       PG8_BAR; PG8_WAIT_L(0); PG8_MMA(1, 0, At, B0); PG8_BAR; PG8_SCHED;
;       PG8_STAGE(PG8_SB(0, 1), b2 + hstep, voffB);
;       PG8_WAIT_V(6); PG8_BAR; PG8_MMA(1, 1, At, B1); PG8_BAR;
.LBB0_874:
	ds_read_b128 v[154:157], v150
	ds_read_b128 v[158:161], v150 offset:1024
	ds_read_b128 v[162:165], v150 offset:2048
	ds_read_b128 v[166:169], v150 offset:3072
	s_add_i32 s59, s24, 2
	s_add_u32 s26, s0, 0x80
	s_addc_u32 s25, s1, 0
	s_cmp_eq_u32 s48, s24
	s_cselect_b32 s24, s4, s26
	s_cselect_b32 s25, s5, s25
	s_cselect_b32 s27, s23, s58
	s_cselect_b32 s26, s22, s57
	s_add_i32 m0, s38, 0xc000
	ds_read_b128 v[170:173], v151
	ds_read_b128 v[174:177], v151 offset:1024
	ds_read_b128 v[178:181], v151 offset:2048
	ds_read_b128 v[182:185], v151 offset:3072
	ds_read_b128 v[188:191], v151 offset:4096
	ds_read_b128 v[194:197], v151 offset:5120
	ds_read_b128 v[198:201], v151 offset:6144
	ds_read_b128 v[202:205], v151 offset:7168
	global_load_lds_dwordx4 v138, s[0:1]
	s_add_i32 m0, s38, 0xe000
	s_nop 0
	global_load_lds_dwordx4 v140, s[0:1]
	ds_read_b128 v[206:209], v152
	ds_read_b128 v[210:213], v152 offset:1024
	ds_read_b128 v[214:217], v152 offset:2048
	ds_read_b128 v[218:221], v152 offset:3072
	s_waitcnt lgkmcnt(0)
	s_barrier
	s_setprio 1
	v_mfma_f32_16x16x32_bf16 v[108:111], v[154:157], v[170:173], v[108:111]
	v_mfma_f32_16x16x32_bf16 v[112:115], v[162:165], v[170:173], v[112:115]
	v_mfma_f32_16x16x32_bf16 v[104:107], v[154:157], v[178:181], v[104:107]
	v_mfma_f32_16x16x32_bf16 v[96:99], v[162:165], v[178:181], v[96:99]
	v_mfma_f32_16x16x32_bf16 v[88:91], v[154:157], v[188:191], v[88:91]
	v_mfma_f32_16x16x32_bf16 v[80:83], v[162:165], v[188:191], v[80:83]
	v_mfma_f32_16x16x32_bf16 v[72:75], v[154:157], v[198:201], v[72:75]
	v_mfma_f32_16x16x32_bf16 v[64:67], v[162:165], v[198:201], v[64:67]
	v_mfma_f32_16x16x32_bf16 v[108:111], v[158:161], v[174:177], v[108:111]
	v_mfma_f32_16x16x32_bf16 v[112:115], v[166:169], v[174:177], v[112:115]
	v_mfma_f32_16x16x32_bf16 v[104:107], v[158:161], v[182:185], v[104:107]
	v_mfma_f32_16x16x32_bf16 v[96:99], v[166:169], v[182:185], v[96:99]
	v_mfma_f32_16x16x32_bf16 v[88:91], v[158:161], v[194:197], v[88:91]
	v_mfma_f32_16x16x32_bf16 v[80:83], v[166:169], v[194:197], v[80:83]
	v_mfma_f32_16x16x32_bf16 v[72:75], v[158:161], v[202:205], v[72:75]
	v_mfma_f32_16x16x32_bf16 v[64:67], v[166:169], v[202:205], v[64:67]
	v_mfma_f32_16x16x32_bf16 v[124:127], v[206:209], v[170:173], v[124:127]
	v_mfma_f32_16x16x32_bf16 v[120:123], v[214:217], v[170:173], v[120:123]
	v_mfma_f32_16x16x32_bf16 v[116:119], v[206:209], v[178:181], v[116:119]
	v_mfma_f32_16x16x32_bf16 v[100:103], v[214:217], v[178:181], v[100:103]
	v_mfma_f32_16x16x32_bf16 v[92:95], v[206:209], v[188:191], v[92:95]
	v_mfma_f32_16x16x32_bf16 v[84:87], v[214:217], v[188:191], v[84:87]
	v_mfma_f32_16x16x32_bf16 v[76:79], v[206:209], v[198:201], v[76:79]
	v_mfma_f32_16x16x32_bf16 v[68:71], v[214:217], v[198:201], v[68:71]
	v_mfma_f32_16x16x32_bf16 v[124:127], v[210:213], v[174:177], v[124:127]
	v_mfma_f32_16x16x32_bf16 v[120:123], v[218:221], v[174:177], v[120:123]
	v_mfma_f32_16x16x32_bf16 v[116:119], v[210:213], v[182:185], v[116:119]
	v_mfma_f32_16x16x32_bf16 v[100:103], v[218:221], v[182:185], v[100:103]
	v_mfma_f32_16x16x32_bf16 v[92:95], v[210:213], v[194:197], v[92:95]
	v_mfma_f32_16x16x32_bf16 v[84:87], v[218:221], v[194:197], v[84:87]
	v_mfma_f32_16x16x32_bf16 v[76:79], v[210:213], v[202:205], v[76:79]
	v_mfma_f32_16x16x32_bf16 v[68:71], v[218:221], v[202:205], v[68:71]
	s_setprio 0
	s_barrier
	s_add_i32 s60, s49, s33
	s_mov_b64 s[92:93], s[26:27]
	s_mov_b32 m0, s60
	global_load_lds_dwordx4 v132, s[26:27]
	s_add_i32 m0, s60, 0x2000
	s_nop 0
	global_load_lds_dwordx4 v128, s[26:27]
	s_mov_b32 m0, s38
	s_mov_b64 s[96:97], s[24:25]
	ds_read_b128 v[170:173], v151 offset:16384
	ds_read_b128 v[174:177], v151 offset:17408
	ds_read_b128 v[178:181], v151 offset:18432
	ds_read_b128 v[182:185], v151 offset:19456
	ds_read_b128 v[188:191], v151 offset:20480
	ds_read_b128 v[194:197], v151 offset:21504
	ds_read_b128 v[198:201], v151 offset:22528
	ds_read_b128 v[202:205], v151 offset:23552
	global_load_lds_dwordx4 v134, s[24:25]
	s_mov_b32 m0, s39
	s_nop 0
	global_load_lds_dwordx4 v130, s[24:25]
	s_add_u32 s26, s26, s6
	s_addc_u32 s27, s27, s7
	s_add_i32 s60, s50, s33
	s_mov_b64 s[100:101], s[26:27]
	s_mov_b32 m0, s60
	global_load_lds_dwordx4 v132, s[26:27]
	s_add_i32 m0, s60, 0x2000
	s_nop 0
	global_load_lds_dwordx4 v128, s[26:27]
	s_waitcnt vmcnt(6)
	s_waitcnt lgkmcnt(0)
	s_barrier
	s_setprio 1
	v_mfma_f32_16x16x32_bf16 v[56:59], v[154:157], v[170:173], v[56:59]
	v_mfma_f32_16x16x32_bf16 v[52:55], v[162:165], v[170:173], v[52:55]
	v_mfma_f32_16x16x32_bf16 v[40:43], v[154:157], v[178:181], v[40:43]
	v_mfma_f32_16x16x32_bf16 v[36:39], v[162:165], v[178:181], v[36:39]
	v_mfma_f32_16x16x32_bf16 v[24:27], v[154:157], v[188:191], v[24:27]
	v_mfma_f32_16x16x32_bf16 v[20:23], v[162:165], v[188:191], v[20:23]
	v_mfma_f32_16x16x32_bf16 v[8:11], v[154:157], v[198:201], v[8:11]
	v_mfma_f32_16x16x32_bf16 v[4:7], v[162:165], v[198:201], v[4:7]
	v_mfma_f32_16x16x32_bf16 v[56:59], v[158:161], v[174:177], v[56:59]
	v_mfma_f32_16x16x32_bf16 v[52:55], v[166:169], v[174:177], v[52:55]
	v_mfma_f32_16x16x32_bf16 v[40:43], v[158:161], v[182:185], v[40:43]
	v_mfma_f32_16x16x32_bf16 v[36:39], v[166:169], v[182:185], v[36:39]
	v_mfma_f32_16x16x32_bf16 v[24:27], v[158:161], v[194:197], v[24:27]
	v_mfma_f32_16x16x32_bf16 v[20:23], v[166:169], v[194:197], v[20:23]
	v_mfma_f32_16x16x32_bf16 v[8:11], v[158:161], v[202:205], v[8:11]
	v_mfma_f32_16x16x32_bf16 v[4:7], v[166:169], v[202:205], v[4:7]
	v_mfma_f32_16x16x32_bf16 v[60:63], v[206:209], v[170:173], v[60:63]
	v_mfma_f32_16x16x32_bf16 v[48:51], v[214:217], v[170:173], v[48:51]
	v_mfma_f32_16x16x32_bf16 v[44:47], v[206:209], v[178:181], v[44:47]
	v_mfma_f32_16x16x32_bf16 v[32:35], v[214:217], v[178:181], v[32:35]
	v_mfma_f32_16x16x32_bf16 v[28:31], v[206:209], v[188:191], v[28:31]
	v_mfma_f32_16x16x32_bf16 v[16:19], v[214:217], v[188:191], v[16:19]
	v_mfma_f32_16x16x32_bf16 v[12:15], v[206:209], v[198:201], v[12:15]
	v_mfma_f32_16x16x32_bf16 v[0:3], v[214:217], v[198:201], v[0:3]
	v_mfma_f32_16x16x32_bf16 v[60:63], v[210:213], v[174:177], v[60:63]
	v_mfma_f32_16x16x32_bf16 v[48:51], v[218:221], v[174:177], v[48:51]
	v_mfma_f32_16x16x32_bf16 v[44:47], v[210:213], v[182:185], v[44:47]
	v_mfma_f32_16x16x32_bf16 v[32:35], v[218:221], v[182:185], v[32:35]
	v_mfma_f32_16x16x32_bf16 v[28:31], v[210:213], v[194:197], v[28:31]
	v_mfma_f32_16x16x32_bf16 v[16:19], v[218:221], v[194:197], v[16:19]
	v_mfma_f32_16x16x32_bf16 v[12:15], v[210:213], v[202:205], v[12:15]
	v_mfma_f32_16x16x32_bf16 v[0:3], v[218:221], v[202:205], v[0:3]
	s_setprio 0
	s_add_i32 s26, 0, 0x18000
	v_add_u32_e32 v166, s26, v149
	s_barrier
; #define PG8_STAGE(bufoff, gbase, voff) do { _Pragma("unroll") for (int _i = 0; _i < 2; ++_i) \
;     __builtin_amdgcn_global_load_lds((const unsigned*)((const char*)(gbase) + (voff)[_i]), (LAS unsigned*)(lds + (bufoff) + ldsw + _i * 8192), 16, 0, 0); } while (0)
; #define PG8_LDA(dst, b, h) do { _Pragma("unroll") for (int m = 0; m < 4; ++m) _Pragma("unroll") for (int k = 0; k < 2; ++k) dst[m][k] = *(const LAS bf16x8*)(lds + PG8_SA(b, h) + aoff + m * 2048 + k * 1024); } while (0)
; #define PG8_LDB(dst, b, h) do { _Pragma("unroll") for (int n = 0; n < 2; ++n) _Pragma("unroll") for (int k = 0; k < 2; ++k) dst[n][k] = *(const LAS bf16x8*)(lds + PG8_SB(b, h) + boff + n * 2048 + k * 1024); } while (0)
; #define PG8_MMA(ai, bj, At, Bt) do { __builtin_amdgcn_s_setprio(1); _Pragma("unroll") for (int m = 0; m < 4; ++m) _Pragma("unroll") for (int n = 0; n < 2; ++n) _Pragma("unroll") for (int k = 0; k < 2; ++k) \
;     acc[ai][bj][m][n] = __builtin_amdgcn_mfma_f32_16x16x32_bf16(Bt[n][k], At[m][k], acc[ai][bj][m][n], 0, 0, 0); __builtin_amdgcn_s_setprio(0); } while (0)
; #define PG8_WAIT_V(n) asm volatile("s_waitcnt vmcnt(" #n ")" ::: "memory")
; #define PG8_WAIT_L(n) asm volatile("s_waitcnt lgkmcnt(" #n ")" ::: "memory")
; #define PG8_BAR __builtin_amdgcn_s_barrier()
; #define PG8_SCHED __builtin_amdgcn_sched_barrier(0)
; template <class Epi>
; __device__ __forceinline__ void gemm_phase(LAS unsigned char* lds, const Gemm g, const StaticOrder& S, const Epi& E) {
;     ...
;       PG8_LDB(B0, 1, 0); PG8_SCHED; PG8_LDA(At, 1, 0); PG8_STAGE(PG8_SA(0, 1), a2 + hstep, voffA);
;       PG8_WAIT_L(8); PG8_BAR; PG8_WAIT_L(0); PG8_MMA(0, 0, At, B0); PG8_BAR; PG8_SCHED;
;       PG8_LDB(B1, 1, 1); PG8_STAGE(PG8_SB(1, 0), b3, voffB);
;       PG8_BAR; PG8_WAIT_L(0); PG8_MMA(0, 1, At, B1); PG8_BAR;
;       PG8_LDA(At, 1, 1); PG8_STAGE(PG8_SA(1, 0), a3, voffA);
;       PG8_BAR; PG8_WAIT_L(0); PG8_MMA(1, 0, At, B0); PG8_BAR; PG8_SCHED;
;       PG8_STAGE(PG8_SB(1, 1), b3 + hstep, voffB);
;       PG8_WAIT_V(6); PG8_BAR; PG8_MMA(1, 1, At, B1); PG8_BAR;
	ds_read_b128 v[154:157], v166
	ds_read_b128 v[158:161], v166 offset:1024
	ds_read_b128 v[162:165], v166 offset:2048
	ds_read_b128 v[166:169], v166 offset:3072
	s_add_u32 s24, s24, s6
	s_addc_u32 s25, s25, s7
	s_mov_b32 m0, s40
	ds_read_b128 v[170:173], v151 offset:32768
	ds_read_b128 v[174:177], v151 offset:33792
	ds_read_b128 v[178:181], v151 offset:34816
	ds_read_b128 v[182:185], v151 offset:35840
	ds_read_b128 v[188:191], v151 offset:36864
	ds_read_b128 v[194:197], v151 offset:37888
	ds_read_b128 v[198:201], v151 offset:38912
	ds_read_b128 v[202:205], v151 offset:39936
	global_load_lds_dwordx4 v134, s[24:25]
	s_mov_b32 m0, s41
	s_nop 0
	global_load_lds_dwordx4 v130, s[24:25]
	s_add_i32 s24, 0, 0x1c000
	v_add_u32_e32 v186, s24, v149
	ds_read_b128 v[206:209], v186
	ds_read_b128 v[210:213], v186 offset:1024
	ds_read_b128 v[214:217], v186 offset:2048
	ds_read_b128 v[218:221], v186 offset:3072
	s_waitcnt lgkmcnt(0)
	s_barrier
	s_setprio 1
	v_mfma_f32_16x16x32_bf16 v[108:111], v[154:157], v[170:173], v[108:111]
	v_mfma_f32_16x16x32_bf16 v[112:115], v[162:165], v[170:173], v[112:115]
	v_mfma_f32_16x16x32_bf16 v[104:107], v[154:157], v[178:181], v[104:107]
	v_mfma_f32_16x16x32_bf16 v[96:99], v[162:165], v[178:181], v[96:99]
	v_mfma_f32_16x16x32_bf16 v[88:91], v[154:157], v[188:191], v[88:91]
	v_mfma_f32_16x16x32_bf16 v[80:83], v[162:165], v[188:191], v[80:83]
	v_mfma_f32_16x16x32_bf16 v[72:75], v[154:157], v[198:201], v[72:75]
	v_mfma_f32_16x16x32_bf16 v[64:67], v[162:165], v[198:201], v[64:67]
	v_mfma_f32_16x16x32_bf16 v[108:111], v[158:161], v[174:177], v[108:111]
	v_mfma_f32_16x16x32_bf16 v[112:115], v[166:169], v[174:177], v[112:115]
	v_mfma_f32_16x16x32_bf16 v[104:107], v[158:161], v[182:185], v[104:107]
	v_mfma_f32_16x16x32_bf16 v[96:99], v[166:169], v[182:185], v[96:99]
	v_mfma_f32_16x16x32_bf16 v[88:91], v[158:161], v[194:197], v[88:91]
	v_mfma_f32_16x16x32_bf16 v[80:83], v[166:169], v[194:197], v[80:83]
	v_mfma_f32_16x16x32_bf16 v[72:75], v[158:161], v[202:205], v[72:75]
	v_mfma_f32_16x16x32_bf16 v[64:67], v[166:169], v[202:205], v[64:67]
	v_mfma_f32_16x16x32_bf16 v[124:127], v[206:209], v[170:173], v[124:127]
	v_mfma_f32_16x16x32_bf16 v[120:123], v[214:217], v[170:173], v[120:123]
	v_mfma_f32_16x16x32_bf16 v[116:119], v[206:209], v[178:181], v[116:119]
	v_mfma_f32_16x16x32_bf16 v[100:103], v[214:217], v[178:181], v[100:103]
	v_mfma_f32_16x16x32_bf16 v[92:95], v[206:209], v[188:191], v[92:95]
	v_mfma_f32_16x16x32_bf16 v[84:87], v[214:217], v[188:191], v[84:87]
	v_mfma_f32_16x16x32_bf16 v[76:79], v[206:209], v[198:201], v[76:79]
	v_mfma_f32_16x16x32_bf16 v[68:71], v[214:217], v[198:201], v[68:71]
	v_mfma_f32_16x16x32_bf16 v[124:127], v[210:213], v[174:177], v[124:127]
	v_mfma_f32_16x16x32_bf16 v[120:123], v[218:221], v[174:177], v[120:123]
	v_mfma_f32_16x16x32_bf16 v[116:119], v[210:213], v[182:185], v[116:119]
	v_mfma_f32_16x16x32_bf16 v[100:103], v[218:221], v[182:185], v[100:103]
	v_mfma_f32_16x16x32_bf16 v[92:95], v[210:213], v[194:197], v[92:95]
	v_mfma_f32_16x16x32_bf16 v[84:87], v[218:221], v[194:197], v[84:87]
	v_mfma_f32_16x16x32_bf16 v[76:79], v[210:213], v[202:205], v[76:79]
	v_mfma_f32_16x16x32_bf16 v[68:71], v[218:221], v[202:205], v[68:71]
	s_setprio 0
	s_barrier
	s_add_i32 s25, s26, s33
	s_add_u32 vcc_lo, s92, s18
	s_addc_u32 vcc_hi, s93, s19
	s_mov_b32 m0, s25
	global_load_lds_dwordx4 v132, vcc
	s_add_i32 m0, s25, 0x2000
	s_nop 0
	global_load_lds_dwordx4 v128, vcc
	s_mov_b32 m0, s43
	s_add_u32 vcc_lo, s96, s18
	s_addc_u32 vcc_hi, s97, s19
	ds_read_b128 v[170:173], v151 offset:49152
	ds_read_b128 v[174:177], v151 offset:50176
	ds_read_b128 v[178:181], v151 offset:51200
	ds_read_b128 v[182:185], v151 offset:52224
	ds_read_b128 v[188:191], v151 offset:53248
	ds_read_b128 v[194:197], v151 offset:54272
	ds_read_b128 v[198:201], v151 offset:55296
	ds_read_b128 v[202:205], v151 offset:56320
	global_load_lds_dwordx4 v134, vcc
	s_mov_b32 m0, s44
	s_nop 0
	global_load_lds_dwordx4 v130, vcc
	s_add_i32 s24, s24, s33
	s_add_u32 vcc_lo, s100, s18
	s_addc_u32 vcc_hi, s101, s19
	s_mov_b32 m0, s24
	s_nop 0
	global_load_lds_dwordx4 v132, vcc
	s_add_i32 m0, s24, 0x2000
	s_nop 0
	global_load_lds_dwordx4 v128, vcc
	s_waitcnt vmcnt(6)
	s_waitcnt lgkmcnt(0)
	s_barrier
	s_setprio 1
	v_mfma_f32_16x16x32_bf16 v[56:59], v[154:157], v[170:173], v[56:59]
	v_mfma_f32_16x16x32_bf16 v[52:55], v[162:165], v[170:173], v[52:55]
	v_mfma_f32_16x16x32_bf16 v[40:43], v[154:157], v[178:181], v[40:43]
	v_mfma_f32_16x16x32_bf16 v[36:39], v[162:165], v[178:181], v[36:39]
	v_mfma_f32_16x16x32_bf16 v[24:27], v[154:157], v[188:191], v[24:27]
	v_mfma_f32_16x16x32_bf16 v[20:23], v[162:165], v[188:191], v[20:23]
	v_mfma_f32_16x16x32_bf16 v[8:11], v[154:157], v[198:201], v[8:11]
	v_mfma_f32_16x16x32_bf16 v[4:7], v[162:165], v[198:201], v[4:7]
	v_mfma_f32_16x16x32_bf16 v[56:59], v[158:161], v[174:177], v[56:59]
	v_mfma_f32_16x16x32_bf16 v[52:55], v[166:169], v[174:177], v[52:55]
	v_mfma_f32_16x16x32_bf16 v[40:43], v[158:161], v[182:185], v[40:43]
	v_mfma_f32_16x16x32_bf16 v[36:39], v[166:169], v[182:185], v[36:39]
	v_mfma_f32_16x16x32_bf16 v[24:27], v[158:161], v[194:197], v[24:27]
	v_mfma_f32_16x16x32_bf16 v[20:23], v[166:169], v[194:197], v[20:23]
	v_mfma_f32_16x16x32_bf16 v[8:11], v[158:161], v[202:205], v[8:11]
	v_mfma_f32_16x16x32_bf16 v[4:7], v[166:169], v[202:205], v[4:7]
	v_mfma_f32_16x16x32_bf16 v[60:63], v[206:209], v[170:173], v[60:63]
	v_mfma_f32_16x16x32_bf16 v[48:51], v[214:217], v[170:173], v[48:51]
	v_mfma_f32_16x16x32_bf16 v[44:47], v[206:209], v[178:181], v[44:47]
	v_mfma_f32_16x16x32_bf16 v[32:35], v[214:217], v[178:181], v[32:35]
	v_mfma_f32_16x16x32_bf16 v[28:31], v[206:209], v[188:191], v[28:31]
	v_mfma_f32_16x16x32_bf16 v[16:19], v[214:217], v[188:191], v[16:19]
	v_mfma_f32_16x16x32_bf16 v[12:15], v[206:209], v[198:201], v[12:15]
	v_mfma_f32_16x16x32_bf16 v[0:3], v[214:217], v[198:201], v[0:3]
	v_mfma_f32_16x16x32_bf16 v[60:63], v[210:213], v[174:177], v[60:63]
	v_mfma_f32_16x16x32_bf16 v[48:51], v[218:221], v[174:177], v[48:51]
	v_mfma_f32_16x16x32_bf16 v[44:47], v[210:213], v[182:185], v[44:47]
	v_mfma_f32_16x16x32_bf16 v[32:35], v[218:221], v[182:185], v[32:35]
	v_mfma_f32_16x16x32_bf16 v[28:31], v[210:213], v[194:197], v[28:31]
	v_mfma_f32_16x16x32_bf16 v[16:19], v[218:221], v[194:197], v[16:19]
	v_mfma_f32_16x16x32_bf16 v[12:15], v[210:213], v[202:205], v[12:15]
	v_mfma_f32_16x16x32_bf16 v[0:3], v[218:221], v[202:205], v[0:3]
	s_setprio 0
	s_add_u32 s0, s0, 0x100
	s_addc_u32 s1, s1, 0
	s_add_u32 s57, s57, 0x100
	s_addc_u32 s58, s58, 0
	s_cmp_ge_i32 s59, s47
	s_mov_b32 s24, s59
	s_barrier
	s_cbranch_scc0 .LBB0_874
	s_branch .LBB0_865
